# rwa: hoisted mu/kkw loads + next-token loads stay in flight; quotas 6/9/19; EpiRes GEMM epilogues with pipelined residual loads (scalar-base addressing, counted vmcnt)
# speedup vs baseline: 1.0642x; 1.0166x over previous
; __device__ __forceinline__ int ltid(int wvs) { int t = (wvs << 6) | (int)__builtin_amdgcn_mbcnt_hi(~0u, __builtin_amdgcn_mbcnt_lo(~0u, 0u)); asm volatile("" : "+v"(t)); return t; }
; __device__ __forceinline__ int lbid() { int b = __builtin_amdgcn_workgroup_id_x(); asm volatile("" : "+s"(b)); return b; }
; __device__ __forceinline__ void phase_rwa(const int wvs, const Params& p, int layer) {
;   const int lane = ltid(wvs) & 63, gw = lbid() * 8 + (ltid(wvs) >> 6);
;   hf* P = (hf*)(p.ws + OFF_BIG); hf* RL1 = (hf*)(p.ws + OFF_RL1); hf* RL3 = (hf*)(p.ws + OFF_RL3); float* INVN = (float*)(p.ws + OFF_INVN);
;   const float* mu = p.in[I_MU] + layer * 1536; const float* kkw = p.in[I_KK] + layer * 384;
;   int t0, tq;
;   if (gw < 768) { t0 = 3 * gw; tq = 3; } else if (gw < 1920) { t0 = 2304 + 11 * (gw - 768); tq = 11; } else { t0 = 14976 + 19 * (gw - 1920); tq = 19; }
.LBB0_1037:
	s_mov_b64 s[2:3], s[0:1]
	s_load_dwordx2 s[6:7], s[2:3], 0xc8
	s_load_dwordx2 s[4:5], s[2:3], 0xf8
	s_load_dwordx2 s[20:21], s[2:3], 0x138
	v_mov_b32_e32 v0, v193
	s_mov_b32 s2, s28
	v_mov_b32_e32 v2, v193
	s_nop 0
	v_ashrrev_i32_e32 v2, 6, v2
	v_lshl_add_u32 v2, s2, 3, v2
	s_movk_i32 s2, 0x2ff
	v_cmp_lt_i32_e32 vcc, s2, v2
	s_and_saveexec_b64 s[2:3], vcc
	s_xor_b64 s[8:9], exec, s[2:3]
	s_cbranch_execz .LBB0_1043
	s_movk_i32 s2, 0x77f
	v_cmp_lt_u32_e32 vcc, s2, v2
	s_and_saveexec_b64 s[2:3], vcc
	s_xor_b64 s[10:11], exec, s[2:3]
	v_mov_b32_e32 v4, 0xffffac00
	v_mov_b32_e32 v5, -1
	v_mad_u64_u32 v[78:79], s[2:3], v2, 19, v[4:5]
	s_or_saveexec_b64 s[10:11], s[10:11]
	v_mov_b32_e32 v4, 19
	s_xor_b64 exec, exec, s[10:11]
	v_mov_b32_e32 v6, 0xfffff700
	v_mov_b32_e32 v7, -1
	v_mov_b32_e32 v4, 9
	v_mad_u64_u32 v[78:79], s[2:3], v2, 9, v[6:7]
	s_or_b64 exec, exec, s[10:11]
.LBB0_1043:
	s_andn2_saveexec_b64 s[8:9], s[8:9]
	v_mul_u32_u24_e32 v78, 6, v2
	v_mov_b32_e32 v4, 6
	s_or_b64 exec, exec, s[8:9]
	v_mul_hi_i32 v2, v78, s89
	v_lshrrev_b32_e32 v3, 31, v2
	v_ashrrev_i32_e32 v2, 11, v2
	v_add_u32_e32 v2, v2, v3
	v_mul_i32_i24_e32 v2, 0x1100, v2
	v_sub_u32_e32 v2, v78, v2
	v_and_b32_e32 v82, 3, v0
	v_cmp_lt_i32_e32 vcc, s29, v2
	s_and_saveexec_b64 s[2:3], vcc
	s_xor_b64 s[8:9], exec, s[2:3]
	s_cbranch_execz .LBB0_1059
	v_cmp_lt_i32_e32 vcc, 1, v82
	s_and_saveexec_b64 s[2:3], vcc
	s_xor_b64 s[10:11], exec, s[2:3]
	s_cbranch_execz .LBB0_1052
	v_add_u32_e32 v2, 0xffffff00, v2
	v_cmp_lt_i32_e32 vcc, 2, v82
	s_and_saveexec_b64 s[2:3], vcc
	s_xor_b64 s[12:13], exec, s[2:3]
	s_movk_i32 s2, 0xfc0
	v_add_u32_e32 v3, 64, v78
	v_cmp_gt_u32_e32 vcc, s2, v2
	s_nop 1
	v_cndmask_b32_e32 v147, -1, v3, vcc
	s_andn2_saveexec_b64 s[12:13], s[12:13]
	v_subrev_u32_e32 v3, 64, v78
	v_cmp_lt_u32_e32 vcc, 63, v2
	s_nop 1
	v_cndmask_b32_e32 v147, -1, v3, vcc
	s_or_b64 exec, exec, s[12:13]

; #define RWA_LOAD(tok_, nb_, pv_, sv_) { const hf* pr_ = P + (size_t)(tok_) * PP + PC_RW; const hf* pn_ = P + (size_t)((nb_) < 0 ? (tok_) : (nb_)) * PP + PC_RW; \
;     _Pragma("unroll") for (int m = 0; m < 24; ++m) { pv_[m] = pr_[lane + 64 * m]; sv_[m] = pn_[lane + 64 * m]; } }
; __device__ __forceinline__ void phase_rwa(const int wvs, const Params& p, int layer) {
;     ...
;   hf* P = (hf*)(p.ws + OFF_BIG); hf* RL1 = (hf*)(p.ws + OFF_RL1); hf* RL3 = (hf*)(p.ws + OFF_RL3); float* INVN = (float*)(p.ws + OFF_INVN);
;   const float* mu = p.in[I_MU] + layer * 1536; const float* kkw = p.in[I_KK] + layer * 384;
;   int t0, tq;
;   if (gw < 768) { t0 = 3 * gw; tq = 3; } else if (gw < 1920) { t0 = 2304 + 11 * (gw - 768); tq = 11; } else { t0 = 14976 + 19 * (gw - 1920); tq = 19; }
;     ...
;   hf pv[24], sv[24]; int nb;
;   RWA_NB(t0, nb) RWA_LOAD(t0, nb, pv, sv)
.LBB0_1065:
	s_or_b64 exec, exec, s[8:9]
	v_readlane_b32 s10, v254, 9
	s_waitcnt lgkmcnt(0)
	s_add_u32 s22, s20, 0x4d0c000
	s_mul_i32 s30, s10, 0x600
	s_addc_u32 s23, s21, 0
	s_lshl_b64 s[2:3], s[30:31], 2
	s_add_u32 s8, s6, s2
	v_mov_b64_e32 v[2:3], s[22:23]
	v_cmp_gt_i32_e32 vcc, 0, v147
	v_and_b32_e32 v32, 63, v0
	s_addc_u32 s9, s7, s3
	v_mad_i64_i32 v[6:7], s[2:3], v78, s51, v[2:3]
	v_cndmask_b32_e32 v0, v147, v78, vcc
	v_lshl_add_u64 v[6:7], v[6:7], 0, s[40:41]
	v_mad_i64_i32 v[2:3], s[2:3], v0, s51, v[2:3]
	v_lshlrev_b32_e32 v0, 1, v32
	v_or_b32_e32 v34, 64, v32
	v_or_b32_e32 v36, 0x80, v32
	v_or_b32_e32 v38, 0xc0, v32
	v_lshl_add_u64 v[2:3], v[2:3], 0, s[40:41]
	v_lshl_add_u64 v[8:9], v[6:7], 0, v[0:1]
	v_lshlrev_b32_e32 v12, 1, v34
	v_mov_b32_e32 v13, v1
	v_lshlrev_b32_e32 v16, 1, v36
	v_mov_b32_e32 v17, v1
	v_lshlrev_b32_e32 v20, 1, v38
	v_mov_b32_e32 v21, v1
	v_or_b32_e32 v40, 0x100, v32
	v_lshl_add_u64 v[10:11], v[2:3], 0, v[0:1]
	v_lshl_add_u64 v[14:15], v[6:7], 0, v[12:13]
	v_lshl_add_u64 v[12:13], v[2:3], 0, v[12:13]
	v_lshl_add_u64 v[18:19], v[6:7], 0, v[16:17]
	v_lshl_add_u64 v[16:17], v[2:3], 0, v[16:17]
	v_lshl_add_u64 v[22:23], v[6:7], 0, v[20:21]
	v_lshl_add_u64 v[20:21], v[2:3], 0, v[20:21]
	global_load_ushort v86, v[8:9], off
	global_load_ushort v151, v[10:11], off
	global_load_ushort v85, v[14:15], off
	global_load_ushort v150, v[12:13], off
	global_load_ushort v84, v[18:19], off
	global_load_ushort v148, v[16:17], off
	global_load_ushort v83, v[22:23], off
	global_load_ushort v149, v[20:21], off
	v_lshlrev_b32_e32 v8, 1, v40
	v_mov_b32_e32 v9, v1
	v_or_b32_e32 v42, 0x140, v32
	v_or_b32_e32 v44, 0x180, v32
	v_or_b32_e32 v46, 0x1c0, v32
	v_lshl_add_u64 v[10:11], v[6:7], 0, v[8:9]
	v_lshl_add_u64 v[8:9], v[2:3], 0, v[8:9]
	v_lshlrev_b32_e32 v12, 1, v42
	v_mov_b32_e32 v13, v1
	v_lshlrev_b32_e32 v16, 1, v44
	v_mov_b32_e32 v17, v1
	v_lshlrev_b32_e32 v20, 1, v46
	v_mov_b32_e32 v21, v1
	v_or_b32_e32 v48, 0x200, v32
	v_lshl_add_u64 v[14:15], v[6:7], 0, v[12:13]
	v_lshl_add_u64 v[12:13], v[2:3], 0, v[12:13]
	v_lshl_add_u64 v[18:19], v[6:7], 0, v[16:17]
	v_lshl_add_u64 v[16:17], v[2:3], 0, v[16:17]
	v_lshl_add_u64 v[22:23], v[6:7], 0, v[20:21]
	v_lshl_add_u64 v[20:21], v[2:3], 0, v[20:21]
	global_load_ushort v90, v[10:11], off
	global_load_ushort v152, v[8:9], off
	global_load_ushort v89, v[14:15], off
	global_load_ushort v153, v[12:13], off
	global_load_ushort v88, v[18:19], off
	global_load_ushort v155, v[16:17], off
	global_load_ushort v87, v[22:23], off
	global_load_ushort v159, v[20:21], off
	v_lshlrev_b32_e32 v8, 1, v48
	v_mov_b32_e32 v9, v1
	v_or_b32_e32 v50, 0x240, v32
	v_or_b32_e32 v52, 0x280, v32
	v_or_b32_e32 v54, 0x2c0, v32
	v_lshl_add_u64 v[10:11], v[6:7], 0, v[8:9]
	v_lshl_add_u64 v[8:9], v[2:3], 0, v[8:9]
	v_lshlrev_b32_e32 v12, 1, v50
	v_mov_b32_e32 v13, v1
	v_lshlrev_b32_e32 v16, 1, v52
	v_mov_b32_e32 v17, v1
	v_lshlrev_b32_e32 v20, 1, v54
	v_mov_b32_e32 v21, v1
	v_or_b32_e32 v56, 0x300, v32
	v_lshl_add_u64 v[14:15], v[6:7], 0, v[12:13]
	v_lshl_add_u64 v[12:13], v[2:3], 0, v[12:13]
	v_lshl_add_u64 v[18:19], v[6:7], 0, v[16:17]
	v_lshl_add_u64 v[16:17], v[2:3], 0, v[16:17]
	v_lshl_add_u64 v[22:23], v[6:7], 0, v[20:21]
	v_lshl_add_u64 v[20:21], v[2:3], 0, v[20:21]
	global_load_ushort v95, v[10:11], off
	global_load_ushort v160, v[8:9], off
	global_load_ushort v94, v[14:15], off
	global_load_ushort v158, v[12:13], off
	global_load_ushort v93, v[18:19], off
	global_load_ushort v157, v[16:17], off
	global_load_ushort v91, v[22:23], off
	global_load_ushort v156, v[20:21], off
	v_lshlrev_b32_e32 v8, 1, v56
	v_mov_b32_e32 v9, v1
	v_or_b32_e32 v58, 0x340, v32
	v_or_b32_e32 v60, 0x380, v32
	v_or_b32_e32 v62, 0x3c0, v32
	v_lshl_add_u64 v[10:11], v[6:7], 0, v[8:9]
	v_lshl_add_u64 v[8:9], v[2:3], 0, v[8:9]
	v_lshlrev_b32_e32 v12, 1, v58
	v_mov_b32_e32 v13, v1
	v_lshlrev_b32_e32 v16, 1, v60
	v_mov_b32_e32 v17, v1
	v_lshlrev_b32_e32 v20, 1, v62
	v_mov_b32_e32 v21, v1
	v_or_b32_e32 v64, 0x400, v32
	v_lshl_add_u64 v[14:15], v[6:7], 0, v[12:13]
	v_lshl_add_u64 v[12:13], v[2:3], 0, v[12:13]
	v_lshl_add_u64 v[18:19], v[6:7], 0, v[16:17]
	v_lshl_add_u64 v[16:17], v[2:3], 0, v[16:17]
	v_lshl_add_u64 v[22:23], v[6:7], 0, v[20:21]
	v_lshl_add_u64 v[20:21], v[2:3], 0, v[20:21]
	global_load_ushort v99, v[10:11], off
	global_load_ushort v146, v[8:9], off
	global_load_ushort v98, v[14:15], off
	global_load_ushort v142, v[12:13], off
	global_load_ushort v97, v[18:19], off
	global_load_ushort v137, v[16:17], off
	global_load_ushort v96, v[22:23], off
	global_load_ushort v135, v[20:21], off
	v_lshlrev_b32_e32 v8, 1, v64
	v_mov_b32_e32 v9, v1
	v_or_b32_e32 v66, 0x440, v32
	v_or_b32_e32 v68, 0x480, v32
	v_or_b32_e32 v70, 0x4c0, v32
	v_lshl_add_u64 v[10:11], v[6:7], 0, v[8:9]
	v_lshl_add_u64 v[8:9], v[2:3], 0, v[8:9]
	v_lshlrev_b32_e32 v12, 1, v66
	v_mov_b32_e32 v13, v1
	v_lshlrev_b32_e32 v16, 1, v68
	v_mov_b32_e32 v17, v1
	v_lshlrev_b32_e32 v20, 1, v70
	v_mov_b32_e32 v21, v1
	v_or_b32_e32 v72, 0x500, v32
	v_lshl_add_u64 v[14:15], v[6:7], 0, v[12:13]
	v_lshl_add_u64 v[12:13], v[2:3], 0, v[12:13]
	v_lshl_add_u64 v[18:19], v[6:7], 0, v[16:17]
	v_lshl_add_u64 v[16:17], v[2:3], 0, v[16:17]
	v_lshl_add_u64 v[22:23], v[6:7], 0, v[20:21]
	v_lshl_add_u64 v[20:21], v[2:3], 0, v[20:21]
	global_load_ushort v103, v[10:11], off
	global_load_ushort v140, v[8:9], off
	global_load_ushort v102, v[14:15], off
	global_load_ushort v139, v[12:13], off
	global_load_ushort v101, v[18:19], off
	global_load_ushort v138, v[16:17], off
	global_load_ushort v100, v[22:23], off
	global_load_ushort v136, v[20:21], off
	v_lshlrev_b32_e32 v8, 1, v72
	v_mov_b32_e32 v9, v1
; #define RWA_LOAD(tok_, nb_, pv_, sv_) { const hf* pr_ = P + (size_t)(tok_) * PP + PC_RW; const hf* pn_ = P + (size_t)((nb_) < 0 ? (tok_) : (nb_)) * PP + PC_RW; \
;     _Pragma("unroll") for (int m = 0; m < 24; ++m) { pv_[m] = pr_[lane + 64 * m]; sv_[m] = pn_[lane + 64 * m]; } }
; __device__ __forceinline__ void phase_rwa(const int wvs, const Params& p, int layer) {
;     ...
;   const float* mu = p.in[I_MU] + layer * 1536; const float* kkw = p.in[I_KK] + layer * 384;
;   int t0, tq;
;   if (gw < 768) { t0 = 3 * gw; tq = 3; } else if (gw < 1920) { t0 = 2304 + 11 * (gw - 768); tq = 11; } else { t0 = 14976 + 19 * (gw - 1920); tq = 19; }
;     ...
;   hf pv[24], sv[24]; int nb;
;   RWA_NB(t0, nb) RWA_LOAD(t0, nb, pv, sv)
; #pragma unroll 1
;   for (int tok = t0; tok < t0 + tq; ++tok) {
;     hf npv[24], nsv[24]; int nnb = -1;
;     if (tok + 1 < t0 + tq) { RWA_NB(tok + 1, nnb) RWA_LOAD(tok + 1, nnb, npv, nsv) }
;     float val[24];
; #pragma unroll
;     for (int m = 0; m < 24; ++m) { const int c = lane + 64 * m; const float a = (float)pv[m], s = nb < 0 ? 0.f : (float)sv[m]; val[m] = a + (s - a) * mu[c]; }
;     float ss[6];
; #pragma unroll
;     for (int m = 6; m < 12; ++m) { const float kv = val[m] * kkw[lane + 64 * m - 384]; ss[m - 6] = wave_sum(kv * kv); }
	v_or_b32_e32 v74, 0x540, v32
	v_or_b32_e32 v76, 0x580, v32
	v_or_b32_e32 v80, 0x5c0, v32
	v_lshl_add_u64 v[10:11], v[6:7], 0, v[8:9]
	v_lshlrev_b32_e32 v12, 1, v74
	v_mov_b32_e32 v13, v1
	v_lshlrev_b32_e32 v16, 1, v76
	v_mov_b32_e32 v17, v1
	v_lshlrev_b32_e32 v20, 1, v80
	v_mov_b32_e32 v21, v1
	v_lshl_add_u64 v[8:9], v[2:3], 0, v[8:9]
	v_lshl_add_u64 v[14:15], v[6:7], 0, v[12:13]
	v_lshl_add_u64 v[12:13], v[2:3], 0, v[12:13]
	v_lshl_add_u64 v[18:19], v[6:7], 0, v[16:17]
	v_lshl_add_u64 v[16:17], v[2:3], 0, v[16:17]
	v_lshl_add_u64 v[6:7], v[6:7], 0, v[20:21]
	v_lshl_add_u64 v[2:3], v[2:3], 0, v[20:21]
	global_load_ushort v107, v[10:11], off
	global_load_ushort v145, v[8:9], off
	global_load_ushort v106, v[14:15], off
	global_load_ushort v144, v[12:13], off
	global_load_ushort v105, v[18:19], off
	global_load_ushort v143, v[16:17], off
	global_load_ushort v104, v[6:7], off
	global_load_ushort v141, v[2:3], off
	s_mul_i32 s30, s10, 0x180
	s_lshl_b64 s[90:91], s[30:31], 2
	s_add_u32 s2, s4, s90
	s_addc_u32 s3, s5, s91
	v_mad_i64_i32 v[2:3], s[4:5], v78, s51, 0
	v_lshlrev_b32_e32 v24, 2, v32
	v_mov_b32_e32 v25, v1
	v_add_u32_e32 v92, v78, v4
	v_cmp_eq_u32_e64 s[4:5], 1, v5
	v_lshl_add_u64 v[4:5], s[8:9], 0, v[24:25]
	v_lshl_add_u64 v[22:23], s[2:3], 0, v[24:25]
	v_mad_i64_i32 v[24:25], s[2:3], v78, 24, v[24:25]
	v_ashrrev_i32_e32 v79, 31, v78
	s_mov_b64 s[2:3], 0xee8c000
	v_add_u32_e32 v30, 1, v78
	v_lshlrev_b32_e32 v6, 2, v64
	v_mov_b32_e32 v7, v1
	v_lshlrev_b32_e32 v8, 2, v66
	v_mov_b32_e32 v9, v1
	v_lshlrev_b32_e32 v10, 2, v68
	v_mov_b32_e32 v11, v1
	v_lshlrev_b32_e32 v12, 2, v70
	v_mov_b32_e32 v13, v1
	v_lshlrev_b32_e32 v14, 2, v72
	v_mov_b32_e32 v15, v1
	v_lshlrev_b32_e32 v16, 2, v74
	v_mov_b32_e32 v17, v1
	v_lshlrev_b32_e32 v18, 2, v76
	v_mov_b32_e32 v19, v1
	v_lshlrev_b32_e32 v20, 2, v80
	v_lshl_add_u64 v[24:25], v[24:25], 0, s[2:3]
	v_mad_i64_i32 v[26:27], s[2:3], v78, s68, 0
	v_lshlrev_b64 v[28:29], 8, v[78:79]
	v_mad_i64_i32 v[30:31], s[2:3], v30, s51, 0
	v_cmp_gt_u32_e64 s[6:7], 6, v32
	v_lshl_add_u64 v[6:7], s[8:9], 0, v[6:7]
	v_lshl_add_u64 v[8:9], s[8:9], 0, v[8:9]
	v_lshl_add_u64 v[10:11], s[8:9], 0, v[10:11]
	v_lshl_add_u64 v[12:13], s[8:9], 0, v[12:13]
	v_lshl_add_u64 v[14:15], s[8:9], 0, v[14:15]
	v_lshl_add_u64 v[16:17], s[8:9], 0, v[16:17]
	v_lshl_add_u64 v[18:19], s[8:9], 0, v[18:19]
	v_lshl_add_u64 v[20:21], s[8:9], 0, v[20:21]
	v_cmp_eq_u32_e64 s[8:9], 1, v32
	v_cmp_eq_u32_e64 s[10:11], 2, v32
	v_cmp_eq_u32_e64 s[12:13], 3, v32
	v_cmp_eq_u32_e64 s[14:15], 4, v32
	v_cmp_eq_u32_e64 s[16:17], 5, v32
	v_or_b32_e32 v26, v26, v0
	v_or_b32_e32 v2, v2, v0
	v_or_b32_e32 v28, v28, v0
	v_or_b32_e32 v30, v30, v0
	s_mov_b64 s[24:25], 0
	v_lshlrev_b32_e32 v0, 1, v32
	v_lshlrev_b32_e32 v32, 1, v34
	v_lshlrev_b32_e32 v34, 1, v36
	v_lshlrev_b32_e32 v36, 1, v38
	v_lshlrev_b32_e32 v38, 1, v40
	v_lshlrev_b32_e32 v40, 1, v42
	v_lshlrev_b32_e32 v42, 1, v44
	v_lshlrev_b32_e32 v44, 1, v46
	v_lshlrev_b32_e32 v46, 1, v48
	v_lshlrev_b32_e32 v48, 1, v50
	v_lshlrev_b32_e32 v50, 1, v52
	v_lshlrev_b32_e32 v52, 1, v54
	v_lshlrev_b32_e32 v54, 1, v56
	v_lshlrev_b32_e32 v56, 1, v58
	v_lshlrev_b32_e32 v58, 1, v60
	v_lshlrev_b32_e32 v60, 1, v62
	v_lshlrev_b32_e32 v62, 1, v64
	v_lshlrev_b32_e32 v64, 1, v66
	v_lshlrev_b32_e32 v66, 1, v68
	v_lshlrev_b32_e32 v68, 1, v70
	v_lshlrev_b32_e32 v70, 1, v72
	v_lshlrev_b32_e32 v72, 1, v74
	v_lshlrev_b32_e32 v74, 1, v76
	v_lshlrev_b32_e32 v76, 1, v80
	global_load_dword v224, v[4:5], off
	global_load_dword v225, v[4:5], off offset:256
	global_load_dword v226, v[4:5], off offset:512
	global_load_dword v227, v[4:5], off offset:768
	global_load_dword v228, v[4:5], off offset:1024
	global_load_dword v229, v[4:5], off offset:1280
	global_load_dword v230, v[4:5], off offset:1536
	global_load_dword v231, v[4:5], off offset:1792
	global_load_dword v232, v[4:5], off offset:2048
	global_load_dword v233, v[4:5], off offset:2304
	global_load_dword v234, v[4:5], off offset:2560
	global_load_dword v235, v[4:5], off offset:2816
	global_load_dword v236, v[4:5], off offset:3072
	global_load_dword v237, v[4:5], off offset:3328
	global_load_dword v238, v[4:5], off offset:3584
	global_load_dword v239, v[4:5], off offset:3840
	global_load_dword v240, v[6:7], off
	global_load_dword v241, v[10:11], off
	global_load_dword v242, v[18:19], off
	global_load_dword v243, v[8:9], off
	global_load_dword v244, v[12:13], off
	global_load_dword v245, v[14:15], off
	global_load_dword v246, v[16:17], off
	global_load_dword v247, v[20:21], off
	global_load_dword v248, v[22:23], off
	global_load_dword v249, v[22:23], off offset:256
	global_load_dword v250, v[22:23], off offset:512
	global_load_dword v251, v[22:23], off offset:768
	global_load_dword v252, v[22:23], off offset:1024
	global_load_dword v253, v[22:23], off offset:1280
	s_waitcnt vmcnt(0)
	s_branch .LBB0_1067
.LBB0_1066:
	s_or_b64 exec, exec, s[48:49]
	s_waitcnt vmcnt(24)
	s_mov_b64 s[2:3], 0x900
	v_lshl_add_u64 v[26:27], v[26:27], 0, s[2:3]
	s_mov_b64 s[2:3], 0x100
	v_lshl_add_u64 v[24:25], v[24:25], 0, 24
	v_lshl_add_u64 v[2:3], v[2:3], 0, s[56:57]
	v_lshl_add_u64 v[28:29], v[28:29], 0, s[2:3]
	v_lshl_add_u64 v[30:31], v[30:31], 0, s[56:57]
	v_mov_b32_e32 v104, v75
	v_mov_b32_e32 v105, v73
	v_mov_b32_e32 v106, v71
	v_mov_b32_e32 v107, v69
	v_mov_b32_e32 v100, v67
	v_mov_b32_e32 v101, v65
	v_mov_b32_e32 v102, v63
	v_mov_b32_e32 v103, v61
	v_mov_b32_e32 v96, v59
	v_mov_b32_e32 v97, v57
	v_mov_b32_e32 v98, v55
	v_mov_b32_e32 v99, v53
	v_mov_b32_e32 v91, v51
	v_mov_b32_e32 v93, v49
	v_mov_b32_e32 v94, v47
	v_mov_b32_e32 v95, v45
	v_mov_b32_e32 v87, v43
	v_mov_b32_e32 v88, v41
	v_mov_b32_e32 v89, v39
	v_mov_b32_e32 v90, v37
	v_mov_b32_e32 v83, v35
	v_mov_b32_e32 v84, v33
	v_mov_b32_e32 v85, v111
	v_mov_b32_e32 v86, v110
	v_mov_b32_e32 v141, v77
	v_mov_b32_e32 v143, v134
	v_mov_b32_e32 v144, v133
	v_mov_b32_e32 v145, v132
	v_mov_b32_e32 v136, v131
	v_mov_b32_e32 v138, v130
	v_mov_b32_e32 v139, v129
	v_mov_b32_e32 v140, v128
	v_mov_b32_e32 v135, v127
	v_mov_b32_e32 v137, v126
	v_mov_b32_e32 v142, v125
	v_mov_b32_e32 v146, v124
	v_mov_b32_e32 v156, v123
	v_mov_b32_e32 v157, v122
	v_mov_b32_e32 v158, v121
	v_mov_b32_e32 v160, v120
	v_mov_b32_e32 v159, v119
	v_mov_b32_e32 v155, v118
	v_mov_b32_e32 v153, v117
	v_mov_b32_e32 v152, v116
	v_mov_b32_e32 v149, v115
	v_mov_b32_e32 v148, v114
	v_mov_b32_e32 v150, v113
	v_mov_b32_e32 v151, v112
	v_mov_b32_e32 v147, v109
	v_mov_b32_e32 v78, v108
	s_movk_i32 s46, 0xfff
	s_andn2_b64 exec, exec, s[24:25]
	s_cbranch_execz .LBB0_1091

; #define RWA_LOAD(tok_, nb_, pv_, sv_) { const hf* pr_ = P + (size_t)(tok_) * PP + PC_RW; const hf* pn_ = P + (size_t)((nb_) < 0 ? (tok_) : (nb_)) * PP + PC_RW; \
;     _Pragma("unroll") for (int m = 0; m < 24; ++m) { pv_[m] = pr_[lane + 64 * m]; sv_[m] = pn_[lane + 64 * m]; } }
; __device__ __forceinline__ void phase_rwa(const int wvs, const Params& p, int layer) {
;     ...
;   for (int tok = t0; tok < t0 + tq; ++tok) {
;     hf npv[24], nsv[24]; int nnb = -1;
;     if (tok + 1 < t0 + tq) { RWA_NB(tok + 1, nnb) RWA_LOAD(tok + 1, nnb, npv, nsv) }
;     float val[24];
; #pragma unroll
;     for (int m = 0; m < 24; ++m) { const int c = lane + 64 * m; const float a = (float)pv[m], s = nb < 0 ? 0.f : (float)sv[m]; val[m] = a + (s - a) * mu[c]; }
;     float ss[6];
; #pragma unroll
;     for (int m = 6; m < 12; ++m) { const float kv = val[m] * kkw[lane + 64 * m - 384]; ss[m - 6] = wave_sum(kv * kv); }
; #pragma unroll
;     for (int m = 0; m < 24; ++m) { const int c = lane + 64 * m;
;       if (m < 18) RL1[(size_t)tok * 1152 + c] = (hf)val[m]; else if (m < 22) P[(size_t)tok * PP + PC_RL2 + (c - 1152)] = (hf)val[m]; else RL3[(size_t)tok * 128 + (c - 1408)] = (hf)val[m]; }
.LBB0_1089:
	s_or_b64 exec, exec, s[26:27]
	v_cvt_f32_f16_e32 v79, v151
	v_cvt_f32_f16_e32 v78, v86
	v_cvt_f32_f16_e32 v138, v138
	v_cvt_f32_f16_e32 v143, v143
	v_cmp_gt_i32_e32 vcc, 0, v147
	v_cvt_f32_f16_e32 v174, v101
	v_cvt_f32_f16_e32 v178, v105
	v_cndmask_b32_e64 v79, v79, 0, vcc
	v_sub_f32_e32 v80, v79, v78
	v_cvt_f32_f16_e32 v79, v150
	v_cvt_f32_f16_e32 v148, v148
	v_cvt_f32_f16_e32 v149, v149
	v_cvt_f32_f16_e32 v152, v152
	v_cvt_f32_f16_e32 v153, v153
	v_cvt_f32_f16_e32 v155, v155
	v_cvt_f32_f16_e32 v78, v85
	v_cvt_f32_f16_e32 v147, v84
	v_cvt_f32_f16_e32 v150, v83
	v_cvt_f32_f16_e32 v151, v90
	v_cvt_f32_f16_e32 v154, v89
	v_cvt_f32_f16_e32 v161, v88
	v_cvt_f32_f16_e32 v159, v159
	v_cvt_f32_f16_e32 v160, v160
	v_cvt_f32_f16_e32 v158, v158
	v_cvt_f32_f16_e32 v157, v157
	v_cvt_f32_f16_e32 v156, v156
	v_cvt_f32_f16_e32 v146, v146
	v_cvt_f32_f16_e32 v142, v142
	v_cvt_f32_f16_e32 v137, v137
	v_cvt_f32_f16_e32 v135, v135
	v_cvt_f32_f16_e32 v140, v140
	v_cvt_f32_f16_e32 v139, v139
	v_cndmask_b32_e64 v138, v138, 0, vcc
	v_cvt_f32_f16_e32 v136, v136
	v_cvt_f32_f16_e32 v145, v145
	v_cvt_f32_f16_e32 v144, v144
	v_cndmask_b32_e64 v143, v143, 0, vcc
	v_cvt_f32_f16_e32 v141, v141
	v_cvt_f32_f16_e32 v162, v87
	v_cvt_f32_f16_e32 v163, v95
	v_cvt_f32_f16_e32 v164, v94
	v_cvt_f32_f16_e32 v165, v93
	v_cvt_f32_f16_e32 v166, v91
	v_cvt_f32_f16_e32 v168, v99
	v_cvt_f32_f16_e32 v169, v98
	v_cvt_f32_f16_e32 v170, v97
	v_cvt_f32_f16_e32 v171, v96
	v_cvt_f32_f16_e32 v172, v103
	v_cvt_f32_f16_e32 v173, v102
	v_sub_f32_e32 v174, v138, v174
	v_cvt_f32_f16_e32 v138, v100
	v_cvt_f32_f16_e32 v176, v107
	v_cvt_f32_f16_e32 v177, v106
	v_sub_f32_e32 v178, v143, v178
	v_cvt_f32_f16_e32 v143, v104
	v_cndmask_b32_e64 v79, v79, 0, vcc
	v_cndmask_b32_e64 v148, v148, 0, vcc
	v_cndmask_b32_e64 v149, v149, 0, vcc
	v_cndmask_b32_e64 v152, v152, 0, vcc
	v_cndmask_b32_e64 v153, v153, 0, vcc
	v_cndmask_b32_e64 v155, v155, 0, vcc
	v_mov_b32_e32 v81, v224
	v_sub_f32_e32 v78, v79, v78
	v_mov_b32_e32 v79, v225
	v_sub_f32_e32 v147, v148, v147
	v_mov_b32_e32 v148, v226
	v_sub_f32_e32 v149, v149, v150
	v_mov_b32_e32 v150, v227
	v_sub_f32_e32 v151, v152, v151
	v_mov_b32_e32 v152, v228
	v_sub_f32_e32 v153, v153, v154
	v_mov_b32_e32 v154, v229
	v_sub_f32_e32 v155, v155, v161
	v_mov_b32_e32 v161, v230
	v_cndmask_b32_e64 v159, v159, 0, vcc
	v_cndmask_b32_e64 v160, v160, 0, vcc
	v_cndmask_b32_e64 v158, v158, 0, vcc
	v_cndmask_b32_e64 v157, v157, 0, vcc
	v_cndmask_b32_e64 v156, v156, 0, vcc
	v_cndmask_b32_e64 v146, v146, 0, vcc
	v_cndmask_b32_e64 v142, v142, 0, vcc
	v_cndmask_b32_e64 v137, v137, 0, vcc
	v_cndmask_b32_e64 v135, v135, 0, vcc
	v_cndmask_b32_e64 v140, v140, 0, vcc
	v_cndmask_b32_e64 v139, v139, 0, vcc
	v_cndmask_b32_e64 v136, v136, 0, vcc
	v_cndmask_b32_e64 v145, v145, 0, vcc
	v_cndmask_b32_e64 v144, v144, 0, vcc
	v_cndmask_b32_e64 v141, v141, 0, vcc
	v_sub_f32_e32 v159, v159, v162
	v_mov_b32_e32 v162, v231
	v_sub_f32_e32 v160, v160, v163
	v_mov_b32_e32 v163, v232
	v_sub_f32_e32 v158, v158, v164
	v_mov_b32_e32 v164, v233
	v_sub_f32_e32 v157, v157, v165
	v_mov_b32_e32 v165, v234
	v_sub_f32_e32 v156, v156, v166
	v_mov_b32_e32 v166, v235
	v_sub_f32_e32 v146, v146, v168
	v_mov_b32_e32 v168, v236
	v_sub_f32_e32 v142, v142, v169
	v_mov_b32_e32 v169, v237
	v_sub_f32_e32 v137, v137, v170
	v_mov_b32_e32 v170, v238
	v_sub_f32_e32 v135, v135, v171
	v_mov_b32_e32 v171, v239
	v_sub_f32_e32 v140, v140, v172
	v_mov_b32_e32 v172, v240
	v_mov_b32_e32 v175, v241
	v_mov_b32_e32 v179, v242
	v_sub_f32_e32 v139, v139, v173
	v_mov_b32_e32 v173, v243
	v_sub_f32_e32 v136, v136, v138
	v_mov_b32_e32 v138, v244
	v_sub_f32_e32 v145, v145, v176
	v_mov_b32_e32 v176, v245
	v_sub_f32_e32 v144, v144, v177
	v_mov_b32_e32 v177, v246
	v_sub_f32_e32 v141, v141, v143
	v_mov_b32_e32 v143, v247
	v_mov_b32_e32 v185, v248
	s_and_b64 s[2:3], exec, s[18:19]
	s_or_b64 s[24:25], s[2:3], s[24:25]
	v_fma_mixlo_f16 v86, v80, v81, v86 op_sel_hi:[0,0,1]
	v_lshl_add_u64 v[80:81], s[20:21], 0, v[26:27]
	v_add_co_u32_e32 v80, vcc, s69, v80
	v_fma_mixlo_f16 v78, v78, v79, v85 op_sel_hi:[0,0,1]
	v_addc_co_u32_e32 v81, vcc, 0, v81, vcc
	global_store_short v[80:81], v78, off offset:128
	v_fma_mixlo_f16 v78, v147, v148, v84 op_sel_hi:[0,0,1]
	global_store_short v[80:81], v78, off offset:256
	v_fma_mixlo_f16 v78, v149, v150, v83 op_sel_hi:[0,0,1]
	global_store_short v[80:81], v78, off offset:384
	v_fma_mix_f32 v184, v155, v161, v88 op_sel_hi:[0,0,1]
	v_fma_mixlo_f16 v78, v151, v152, v90 op_sel_hi:[0,0,1]
	global_store_short v[80:81], v78, off offset:512
	v_fma_mixlo_f16 v78, v153, v154, v89 op_sel_hi:[0,0,1]
	global_store_short v[80:81], v78, off offset:640
	v_fma_mixlo_f16 v78, v155, v161, v88 op_sel_hi:[0,0,1]
	global_store_short v[80:81], v78, off offset:768
	global_store_short v[80:81], v86, off
	v_fma_mix_f32 v183, v159, v162, v87 op_sel_hi:[0,0,1]
	v_fma_mixlo_f16 v78, v159, v162, v87 op_sel_hi:[0,0,1]
	v_fma_mix_f32 v182, v160, v163, v95 op_sel_hi:[0,0,1]
	global_store_short v[80:81], v78, off offset:896
	v_fma_mix_f32 v181, v158, v164, v94 op_sel_hi:[0,0,1]
	v_fma_mixlo_f16 v78, v160, v163, v95 op_sel_hi:[0,0,1]
	v_fma_mix_f32 v180, v157, v165, v93 op_sel_hi:[0,0,1]
	global_store_short v[80:81], v78, off offset:1024
	v_fma_mixlo_f16 v78, v158, v164, v94 op_sel_hi:[0,0,1]
	global_store_short v[80:81], v78, off offset:1152
	v_fma_mixlo_f16 v78, v157, v165, v93 op_sel_hi:[0,0,1]
	global_store_short v[80:81], v78, off offset:1280
	v_fma_mixlo_f16 v78, v156, v166, v91 op_sel_hi:[0,0,1]
	global_store_short v[80:81], v78, off offset:1408
	v_fma_mixlo_f16 v78, v146, v168, v99 op_sel_hi:[0,0,1]
	global_store_short v[80:81], v78, off offset:1536
; __device__ __forceinline__ void phase_rwa(const int wvs, const Params& p, int layer) {
;     ...
;     for (int m = 0; m < 24; ++m) { const int c = lane + 64 * m; const float a = (float)pv[m], s = nb < 0 ? 0.f : (float)sv[m]; val[m] = a + (s - a) * mu[c]; }
;     float ss[6];
; #pragma unroll
;     for (int m = 6; m < 12; ++m) { const float kv = val[m] * kkw[lane + 64 * m - 384]; ss[m - 6] = wave_sum(kv * kv); }
; #pragma unroll
;     for (int m = 0; m < 24; ++m) { const int c = lane + 64 * m;
;       if (m < 18) RL1[(size_t)tok * 1152 + c] = (hf)val[m]; else if (m < 22) P[(size_t)tok * PP + PC_RL2 + (c - 1152)] = (hf)val[m]; else RL3[(size_t)tok * 128 + (c - 1408)] = (hf)val[m]; }
;     if (lane < 6) { float s = ss[0];
; #pragma unroll
;       for (int q = 1; q < 6; ++q) s = lane == q ? ss[q] : s;
;       INVN[(size_t)tok * 6 + lane] = rsqrtf(s + 1e-6f); }
	v_fma_mixlo_f16 v78, v142, v169, v98 op_sel_hi:[0,0,1]
	global_store_short v[80:81], v78, off offset:1664
	v_fma_mixlo_f16 v78, v137, v170, v97 op_sel_hi:[0,0,1]
	global_store_short v[80:81], v78, off offset:1792
	v_fma_mixlo_f16 v78, v135, v171, v96 op_sel_hi:[0,0,1]
	global_store_short v[80:81], v78, off offset:1920
	v_fma_mixlo_f16 v78, v140, v172, v103 op_sel_hi:[0,0,1]
	global_store_short v[80:81], v78, off offset:2048
	v_fma_mixlo_f16 v78, v139, v173, v102 op_sel_hi:[0,0,1]
	global_store_short v[80:81], v78, off offset:2176
	v_lshl_add_u64 v[78:79], s[20:21], 0, v[2:3]
	v_fma_mix_f32 v167, v156, v166, v91 op_sel_hi:[0,0,1]
	v_add_co_u32_e32 v78, vcc, s55, v78
	v_mul_f32_e32 v184, v184, v185
	v_mul_f32_e32 v185, v184, v184
	v_fma_mixlo_f16 v80, v174, v175, v101 op_sel_hi:[0,0,1]
	v_addc_co_u32_e32 v79, vcc, 0, v79, vcc
	v_mov_b32_dpp v185, v185 quad_perm:[1,0,3,2] row_mask:0xf bank_mask:0xf bound_ctrl:1
	v_fmac_f32_e32 v185, v184, v184
	global_store_short v[78:79], v80, off offset:3584
	v_fma_mixlo_f16 v80, v136, v138, v100 op_sel_hi:[0,0,1]
	v_add_f32_dpp v184, v185, v185 quad_perm:[2,3,0,1] row_mask:0xf bank_mask:0xf bound_ctrl:1
	global_store_short v[78:79], v80, off offset:3712
	v_fma_mixlo_f16 v80, v145, v176, v107 op_sel_hi:[0,0,1]
	v_add_f32_dpp v184, v184, v184 row_half_mirror row_mask:0xf bank_mask:0xf bound_ctrl:1
	global_store_short v[78:79], v80, off offset:3840
	v_fma_mixlo_f16 v80, v144, v177, v106 op_sel_hi:[0,0,1]
	v_add_f32_dpp v184, v184, v184 row_mirror row_mask:0xf bank_mask:0xf bound_ctrl:1
	global_store_short v[78:79], v80, off offset:3968
	v_readlane_b32 s18, v184, 0
	v_readlane_b32 s3, v184, 16
	v_readlane_b32 s19, v184, 32
	v_readlane_b32 s30, v184, 48
	v_mov_b32_e32 v184, v249
	v_lshl_add_u64 v[78:79], s[20:21], 0, v[28:29]
	v_add_co_u32_e32 v78, vcc, 0xea4c000, v78
	v_fma_mixlo_f16 v80, v178, v179, v105 op_sel_hi:[0,0,1]
	s_nop 0
	v_addc_co_u32_e32 v79, vcc, 0, v79, vcc
	global_store_short v[78:79], v80, off
	v_fma_mixlo_f16 v80, v141, v143, v104 op_sel_hi:[0,0,1]
	global_store_short v[78:79], v80, off offset:128
	v_mul_f32_e32 v183, v183, v184
	v_mul_f32_e32 v184, v183, v183
	s_nop 1
	v_mov_b32_dpp v184, v184 quad_perm:[1,0,3,2] row_mask:0xf bank_mask:0xf bound_ctrl:1
	v_fmac_f32_e32 v184, v183, v183
	s_nop 1
	v_add_f32_dpp v183, v184, v184 quad_perm:[2,3,0,1] row_mask:0xf bank_mask:0xf bound_ctrl:1
	s_nop 1
	v_add_f32_dpp v183, v183, v183 row_half_mirror row_mask:0xf bank_mask:0xf bound_ctrl:1
	s_nop 1
	v_add_f32_dpp v183, v183, v183 row_mirror row_mask:0xf bank_mask:0xf bound_ctrl:1
	s_nop 0
	v_readlane_b32 s26, v183, 0
	v_readlane_b32 s54, v183, 16
	v_readlane_b32 s27, v183, 32
	v_readlane_b32 s74, v183, 48
	v_mov_b32_e32 v183, v250
	v_mul_f32_e32 v182, v182, v183
	v_mul_f32_e32 v183, v182, v182
	s_nop 1
	v_mov_b32_dpp v183, v183 quad_perm:[1,0,3,2] row_mask:0xf bank_mask:0xf bound_ctrl:1
	v_fmac_f32_e32 v183, v182, v182
	s_nop 1
	v_add_f32_dpp v182, v183, v183 quad_perm:[2,3,0,1] row_mask:0xf bank_mask:0xf bound_ctrl:1
	s_nop 1
	v_add_f32_dpp v182, v182, v182 row_half_mirror row_mask:0xf bank_mask:0xf bound_ctrl:1
	s_nop 1
	v_add_f32_dpp v182, v182, v182 row_mirror row_mask:0xf bank_mask:0xf bound_ctrl:1
	s_nop 0
	v_readlane_b32 s58, v182, 0
	v_readlane_b32 s75, v182, 16
	v_readlane_b32 s59, v182, 32
	v_readlane_b32 s76, v182, 48
	v_mov_b32_e32 v182, v251
	v_mul_f32_e32 v181, v181, v182
	v_mul_f32_e32 v182, v181, v181
	s_nop 1
	v_mov_b32_dpp v182, v182 quad_perm:[1,0,3,2] row_mask:0xf bank_mask:0xf bound_ctrl:1
	v_fmac_f32_e32 v182, v181, v181
	s_nop 1
	v_add_f32_dpp v181, v182, v182 quad_perm:[2,3,0,1] row_mask:0xf bank_mask:0xf bound_ctrl:1
	s_nop 1
	v_add_f32_dpp v181, v181, v181 row_half_mirror row_mask:0xf bank_mask:0xf bound_ctrl:1
	s_nop 1
	v_add_f32_dpp v181, v181, v181 row_mirror row_mask:0xf bank_mask:0xf bound_ctrl:1
	s_nop 0
	v_readlane_b32 s92, v181, 0
	v_readlane_b32 s77, v181, 16
	v_readlane_b32 s93, v181, 32
	v_readlane_b32 s78, v181, 48
	v_mov_b32_e32 v181, v252
	v_mul_f32_e32 v180, v180, v181
	v_mul_f32_e32 v181, v180, v180
	s_nop 1
	v_mov_b32_dpp v181, v181 quad_perm:[1,0,3,2] row_mask:0xf bank_mask:0xf bound_ctrl:1
	v_fmac_f32_e32 v181, v180, v180
	s_nop 1
	v_add_f32_dpp v180, v181, v181 quad_perm:[2,3,0,1] row_mask:0xf bank_mask:0xf bound_ctrl:1
	s_nop 1
	v_add_f32_dpp v180, v180, v180 row_half_mirror row_mask:0xf bank_mask:0xf bound_ctrl:1
	s_nop 1
	v_add_f32_dpp v180, v180, v180 row_mirror row_mask:0xf bank_mask:0xf bound_ctrl:1
	s_nop 0
	v_readlane_b32 s94, v180, 0
	v_readlane_b32 s79, v180, 16
	v_readlane_b32 s95, v180, 32
	v_readlane_b32 s80, v180, 48
	v_mov_b32_e32 v180, v253
	v_mul_f32_e32 v167, v167, v180
	v_mul_f32_e32 v180, v167, v167
	s_nop 1
	v_mov_b32_dpp v180, v180 quad_perm:[1,0,3,2] row_mask:0xf bank_mask:0xf bound_ctrl:1
	v_fmac_f32_e32 v180, v167, v167
	s_nop 1
	v_add_f32_dpp v167, v180, v180 quad_perm:[2,3,0,1] row_mask:0xf bank_mask:0xf bound_ctrl:1
	s_nop 1
	v_add_f32_dpp v167, v167, v167 row_half_mirror row_mask:0xf bank_mask:0xf bound_ctrl:1
	s_nop 1
	v_add_f32_dpp v167, v167, v167 row_mirror row_mask:0xf bank_mask:0xf bound_ctrl:1
	s_nop 0
	v_readlane_b32 s44, v167, 0
	v_readlane_b32 s2, v167, 16
	v_readlane_b32 s45, v167, 32
	v_readlane_b32 s36, v167, 48
	s_and_saveexec_b64 s[48:49], s[6:7]
	s_cbranch_execz .LBB0_1066
	v_mov_b32_e32 v78, s2
	v_mov_b32_e32 v79, s36
	v_pk_add_f32 v[78:79], s[44:45], v[78:79]
	s_nop 0
	v_add_f32_e32 v80, v78, v79
	v_mov_b32_e32 v78, s79
	v_mov_b32_e32 v79, s80
	v_pk_add_f32 v[78:79], s[94:95], v[78:79]
	s_nop 0
	v_add_f32_e32 v81, v78, v79
	v_mov_b32_e32 v78, s77
	v_mov_b32_e32 v79, s78
	v_pk_add_f32 v[78:79], s[92:93], v[78:79]
	s_nop 0
	v_add_f32_e32 v83, v78, v79
	v_mov_b32_e32 v78, s75
	v_mov_b32_e32 v79, s76
	v_pk_add_f32 v[78:79], s[58:59], v[78:79]
	s_nop 0
	v_add_f32_e32 v84, v78, v79
	v_mov_b32_e32 v78, s54
	v_mov_b32_e32 v79, s74
	v_pk_add_f32 v[78:79], s[26:27], v[78:79]
	s_nop 0
	v_add_f32_e32 v85, v78, v79
	v_mov_b32_e32 v78, s3
	v_mov_b32_e32 v79, s30
	v_pk_add_f32 v[78:79], s[18:19], v[78:79]
	s_nop 0
	v_add_f32_e32 v78, v78, v79
	v_cndmask_b32_e64 v78, v78, v85, s[8:9]
	v_cndmask_b32_e64 v78, v78, v84, s[10:11]
	v_cndmask_b32_e64 v78, v78, v83, s[12:13]
	v_cndmask_b32_e64 v78, v78, v81, s[14:15]
	v_cndmask_b32_e64 v78, v78, v80, s[16:17]
	v_add_f32_e32 v78, 0x358637bd, v78
	v_mul_f32_e32 v79, 0x4b800000, v78
	v_cmp_gt_f32_e32 vcc, s34, v78
	s_nop 1
	v_cndmask_b32_e32 v78, v78, v79, vcc
	v_rsq_f32_e32 v78, v78
	s_nop 0
	v_mul_f32_e32 v79, 0x45800000, v78
	v_cndmask_b32_e32 v80, v78, v79, vcc
	v_lshl_add_u64 v[78:79], s[20:21], 0, v[24:25]
	global_store_dword v[78:79], v80, off
	s_branch .LBB0_1066

;     __device__ __forceinline__ void operator()(const f32x4 (&acc)[2][2][4][2], const Unit& u, int wr, int wc, int fr, int fq) const {
;     ...
;         const int col0 = u.pn * BM + wc * 32 + 4 * fq, rloc = wr * 64 + fr;
; #pragma unroll
;         for (int bj = 0; bj < 2; ++bj)
; #pragma unroll
;             for (int n = 0; n < 2; ++n) { const f32x4 gv = *(const f32x4*)(gp + col0 + bj * HALF + n * 16);
; #pragma unroll
;                 for (int ai = 0; ai < 2; ++ai)
; #pragma unroll
;                     for (int m = 0; m < 4; ++m) { const size_t ro = (size_t)(rloc + ai * HALF + m * 16) * DM + col0 + bj * HALF + n * 16;
;                         if (atomic) { const f32x4 v = gv * acc[ai][bj][m][n];
; #pragma unroll
;                             for (int j = 0; j < 4; ++j) unsafeAtomicAdd(xout + ro + j, v[j]); }
;                         else { const f32x4 xi = *(const f32x4*)(xin + ro); *(f32x4*)(xout + ro) = xi + gv * acc[ai][bj][m][n]; } }
;                 asm volatile("" ::: "memory"); }
.LBB0_1496:
	s_waitcnt lgkmcnt(0)
	s_add_u32 s2, s10, s74
	s_addc_u32 s7, s11, 0
	s_ashr_i32 s25, s24, 31
	s_lshl_b64 s[20:21], s[24:25], 12
	s_add_u32 s10, s18, s20
	s_addc_u32 s11, s19, s21
	s_add_u32 s8, s8, s20
	s_addc_u32 s9, s9, s21
	s_lshl_b64 s[18:19], s[22:23], 2
	s_add_u32 s18, s2, s18
	s_addc_u32 s19, s7, s19
	s_lshl_b32 s2, s90, 8
	s_or_b32 s2, s2, s81
	v_add_u32_e32 v144, s80, v130
	v_lshl_add_u32 v142, v131, 2, s2
	v_ashrrev_i32_e32 v145, 31, v144
	v_ashrrev_i32_e32 v143, 31, v142
	v_lshlrev_b64 v[144:145], 10, v[144:145]
	v_lshl_add_u64 v[130:131], v[142:143], 2, s[18:19]
	s_mov_b64 s[18:19], 0x26d2000
	s_mov_b32 s2, 0x26d2000
	v_lshl_add_u64 v[142:143], v[144:145], 0, v[142:143]
	v_lshl_add_u64 v[140:141], v[130:131], 0, s[18:19]
	v_add_co_u32_e32 v130, vcc, s2, v130
	v_lshlrev_b64 v[144:145], 2, v[142:143]
	s_nop 0
	v_addc_co_u32_e32 v131, vcc, 0, v131, vcc
	v_lshl_add_u64 v[142:143], s[10:11], 0, v[144:145]
	v_mov_b32_e32 v200, v144
	v_add_u32_e32 v202, 0x10000, v200
	v_add_u32_e32 v204, 0x20000, v200
	v_add_u32_e32 v206, 0x30000, v200
	v_add_u32_e32 v208, 0x80000, v200
	v_add_u32_e32 v210, 0x90000, v200
	v_add_u32_e32 v212, 0xa0000, v200
	v_add_u32_e32 v214, 0xb0000, v200
	global_load_dwordx4 v[130:133], v[140:141], off
	global_load_dwordx4 v[142:145], v[140:141], off offset:64
	global_load_dwordx4 v[236:239], v200, s[10:11]
	global_load_dwordx4 v[240:243], v202, s[10:11]
	global_load_dwordx4 v[244:247], v204, s[10:11]
	global_load_dwordx4 v[248:251], v206, s[10:11]
	global_load_dwordx4 v[150:153], v208, s[10:11]
	s_waitcnt vmcnt(4)
	v_pk_fma_f32 v[128:129], v[128:129], v[132:133], v[238:239]
	v_pk_fma_f32 v[126:127], v[126:127], v[130:131], v[236:237]
	global_store_dwordx4 v200, v[126:129], s[8:9]
	global_load_dwordx4 v[236:239], v210, s[10:11]
	s_waitcnt vmcnt(5)
	v_pk_fma_f32 v[124:125], v[124:125], v[132:133], v[242:243]
	v_pk_fma_f32 v[122:123], v[122:123], v[130:131], v[240:241]
	global_store_dwordx4 v202, v[122:125], s[8:9]
	global_load_dwordx4 v[240:243], v212, s[10:11]
	global_load_dwordx4 v[126:129], v214, s[10:11]
	s_waitcnt vmcnt(7)
	v_pk_fma_f32 v[120:121], v[120:121], v[132:133], v[246:247]
	v_pk_fma_f32 v[118:119], v[118:119], v[130:131], v[244:245]
	global_store_dwordx4 v204, v[118:121], s[8:9]
	global_load_dwordx4 v[244:247], v200, s[10:11] offset:64
	global_load_dwordx4 v[122:125], v202, s[10:11] offset:64
	s_waitcnt vmcnt(9)
	v_pk_fma_f32 v[116:117], v[116:117], v[132:133], v[250:251]
	v_pk_fma_f32 v[114:115], v[114:115], v[130:131], v[248:249]
	global_store_dwordx4 v206, v[114:117], s[8:9]
	global_load_dwordx4 v[248:251], v204, s[10:11] offset:64
	global_load_dwordx4 v[118:121], v206, s[10:11] offset:64
	s_waitcnt vmcnt(11)
	v_pk_fma_f32 v[112:113], v[112:113], v[132:133], v[152:153]
	v_pk_fma_f32 v[110:111], v[110:111], v[130:131], v[150:151]
	global_store_dwordx4 v208, v[110:113], s[8:9]
	global_load_dwordx4 v[150:153], v208, s[10:11] offset:64
	global_load_dwordx4 v[114:117], v210, s[10:11] offset:64
	s_waitcnt vmcnt(12)
	v_pk_fma_f32 v[108:109], v[108:109], v[132:133], v[238:239]
	v_pk_fma_f32 v[106:107], v[106:107], v[130:131], v[236:237]
	global_store_dwordx4 v210, v[106:109], s[8:9]
	global_load_dwordx4 v[236:239], v212, s[10:11] offset:64
	global_load_dwordx4 v[110:113], v214, s[10:11] offset:64
	s_waitcnt vmcnt(13)
	v_pk_fma_f32 v[104:105], v[104:105], v[132:133], v[242:243]
	v_pk_fma_f32 v[102:103], v[102:103], v[130:131], v[240:241]
	global_store_dwordx4 v212, v[102:105], s[8:9]
	global_load_dwordx4 v[240:243], v200, s[10:11] offset:512
	global_load_dwordx4 v[106:109], v202, s[10:11] offset:512
	s_waitcnt vmcnt(15)
	v_pk_fma_f32 v[88:89], v[88:89], v[132:133], v[128:129]
	v_pk_fma_f32 v[86:87], v[86:87], v[130:131], v[126:127]
	global_store_dwordx4 v214, v[86:89], s[8:9]
	global_load_dwordx4 v[130:133], v[140:141], off offset:512
	global_load_dwordx4 v[126:129], v204, s[10:11] offset:512
	global_load_dwordx4 v[102:105], v206, s[10:11] offset:512
	s_waitcnt vmcnt(17)
	v_pk_fma_f32 v[100:101], v[100:101], v[144:145], v[246:247]
	v_pk_fma_f32 v[98:99], v[98:99], v[142:143], v[244:245]
	global_store_dwordx4 v200, v[98:101], s[8:9] offset:64
	global_load_dwordx4 v[244:247], v208, s[10:11] offset:512
	s_waitcnt vmcnt(18)
	v_pk_fma_f32 v[96:97], v[96:97], v[144:145], v[124:125]
	v_pk_fma_f32 v[94:95], v[94:95], v[142:143], v[122:123]
	global_store_dwordx4 v202, v[94:97], s[8:9] offset:64
	global_load_dwordx4 v[86:89], v210, s[10:11] offset:512
	s_waitcnt vmcnt(18)
	v_pk_fma_f32 v[92:93], v[92:93], v[144:145], v[250:251]
	v_pk_fma_f32 v[90:91], v[90:91], v[142:143], v[248:249]
	global_store_dwordx4 v204, v[90:93], s[8:9] offset:64
	global_load_dwordx4 v[122:125], v212, s[10:11] offset:512
	s_waitcnt vmcnt(19)
;     __device__ __forceinline__ void operator()(const f32x4 (&acc)[2][2][4][2], const Unit& u, int wr, int wc, int fr, int fq) const {
;     ...
;         const int col0 = u.pn * BM + wc * 32 + 4 * fq, rloc = wr * 64 + fr;
; #pragma unroll
;         for (int bj = 0; bj < 2; ++bj)
; #pragma unroll
;             for (int n = 0; n < 2; ++n) { const f32x4 gv = *(const f32x4*)(gp + col0 + bj * HALF + n * 16);
; #pragma unroll
;                 for (int ai = 0; ai < 2; ++ai)
; #pragma unroll
;                     for (int m = 0; m < 4; ++m) { const size_t ro = (size_t)(rloc + ai * HALF + m * 16) * DM + col0 + bj * HALF + n * 16;
;                         if (atomic) { const f32x4 v = gv * acc[ai][bj][m][n];
; #pragma unroll
;                             for (int j = 0; j < 4; ++j) unsafeAtomicAdd(xout + ro + j, v[j]); }
;                         else { const f32x4 xi = *(const f32x4*)(xin + ro); *(f32x4*)(xout + ro) = xi + gv * acc[ai][bj][m][n]; } }
;                 asm volatile("" ::: "memory"); }
	v_pk_fma_f32 v[84:85], v[84:85], v[144:145], v[120:121]
	v_pk_fma_f32 v[82:83], v[82:83], v[142:143], v[118:119]
	global_store_dwordx4 v206, v[82:85], s[8:9] offset:64
	global_load_dwordx4 v[98:101], v214, s[10:11] offset:512
	s_waitcnt vmcnt(19)
	v_pk_fma_f32 v[80:81], v[80:81], v[144:145], v[152:153]
	v_pk_fma_f32 v[78:79], v[78:79], v[142:143], v[150:151]
	global_store_dwordx4 v208, v[78:81], s[8:9] offset:64
	global_load_dwordx4 v[248:251], v200, s[10:11] offset:576
	s_waitcnt vmcnt(20)
	v_pk_fma_f32 v[72:73], v[72:73], v[144:145], v[116:117]
	v_pk_fma_f32 v[70:71], v[70:71], v[142:143], v[114:115]
	global_store_dwordx4 v210, v[70:73], s[8:9] offset:64
	global_load_dwordx4 v[94:97], v202, s[10:11] offset:576
	s_waitcnt vmcnt(20)
	v_pk_fma_f32 v[64:65], v[64:65], v[144:145], v[238:239]
	v_pk_fma_f32 v[62:63], v[62:63], v[142:143], v[236:237]
	global_store_dwordx4 v212, v[62:65], s[8:9] offset:64
	global_load_dwordx4 v[118:121], v204, s[10:11] offset:576
	s_waitcnt vmcnt(21)
	v_pk_fma_f32 v[56:57], v[56:57], v[144:145], v[112:113]
	v_pk_fma_f32 v[54:55], v[54:55], v[142:143], v[110:111]
	global_store_dwordx4 v214, v[54:57], s[8:9] offset:64
	global_load_dwordx4 v[142:145], v[140:141], off offset:576
	global_load_dwordx4 v[90:93], v206, s[10:11] offset:576
	s_waitcnt vmcnt(19)
	v_pk_fma_f32 v[76:77], v[76:77], v[132:133], v[242:243]
	v_pk_fma_f32 v[74:75], v[74:75], v[130:131], v[240:241]
	global_store_dwordx4 v200, v[74:77], s[8:9] offset:512
	global_load_dwordx4 v[150:153], v208, s[10:11] offset:576
	s_waitcnt vmcnt(21)
	v_pk_fma_f32 v[68:69], v[68:69], v[132:133], v[108:109]
	v_pk_fma_f32 v[66:67], v[66:67], v[130:131], v[106:107]
	global_store_dwordx4 v202, v[66:69], s[8:9] offset:512
	global_load_dwordx4 v[82:85], v210, s[10:11] offset:576
	s_waitcnt vmcnt(22)
	v_pk_fma_f32 v[60:61], v[60:61], v[132:133], v[128:129]
	v_pk_fma_f32 v[58:59], v[58:59], v[130:131], v[126:127]
	global_store_dwordx4 v204, v[58:61], s[8:9] offset:512
	global_load_dwordx4 v[114:117], v212, s[10:11] offset:576
	s_waitcnt vmcnt(23)
	v_pk_fma_f32 v[52:53], v[52:53], v[132:133], v[104:105]
	v_pk_fma_f32 v[50:51], v[50:51], v[130:131], v[102:103]
	global_store_dwordx4 v206, v[50:53], s[8:9] offset:512
	global_load_dwordx4 v[78:81], v214, s[10:11] offset:576
	s_waitcnt vmcnt(23)
	v_pk_fma_f32 v[44:45], v[44:45], v[132:133], v[246:247]
	v_pk_fma_f32 v[42:43], v[42:43], v[130:131], v[244:245]
	global_store_dwordx4 v208, v[42:45], s[8:9] offset:512
	s_waitcnt vmcnt(22)
	v_pk_fma_f32 v[36:37], v[36:37], v[132:133], v[88:89]
	v_pk_fma_f32 v[34:35], v[34:35], v[130:131], v[86:87]
	global_store_dwordx4 v210, v[34:37], s[8:9] offset:512
	s_waitcnt vmcnt(21)
	v_pk_fma_f32 v[28:29], v[28:29], v[132:133], v[124:125]
	v_pk_fma_f32 v[26:27], v[26:27], v[130:131], v[122:123]
	global_store_dwordx4 v212, v[26:29], s[8:9] offset:512
	s_waitcnt vmcnt(20)
	v_pk_fma_f32 v[20:21], v[20:21], v[132:133], v[100:101]
	v_pk_fma_f32 v[18:19], v[18:19], v[130:131], v[98:99]
	global_store_dwordx4 v214, v[18:21], s[8:9] offset:512
	s_waitcnt vmcnt(13)
	v_pk_fma_f32 v[48:49], v[48:49], v[144:145], v[250:251]
	v_pk_fma_f32 v[46:47], v[46:47], v[142:143], v[248:249]
	global_store_dwordx4 v200, v[46:49], s[8:9] offset:576
	s_waitcnt vmcnt(14)
	v_pk_fma_f32 v[40:41], v[40:41], v[144:145], v[96:97]
	v_pk_fma_f32 v[38:39], v[38:39], v[142:143], v[94:95]
	global_store_dwordx4 v202, v[38:41], s[8:9] offset:576
	s_waitcnt vmcnt(15)
	v_pk_fma_f32 v[32:33], v[32:33], v[144:145], v[120:121]
	v_pk_fma_f32 v[30:31], v[30:31], v[142:143], v[118:119]
	global_store_dwordx4 v204, v[30:33], s[8:9] offset:576
	s_waitcnt vmcnt(15)
	v_pk_fma_f32 v[24:25], v[24:25], v[144:145], v[92:93]
	v_pk_fma_f32 v[22:23], v[22:23], v[142:143], v[90:91]
	global_store_dwordx4 v206, v[22:25], s[8:9] offset:576
	s_waitcnt vmcnt(14)
	v_pk_fma_f32 v[16:17], v[16:17], v[144:145], v[152:153]
	v_pk_fma_f32 v[14:15], v[14:15], v[142:143], v[150:151]
	global_store_dwordx4 v208, v[14:17], s[8:9] offset:576
	s_waitcnt vmcnt(13)
	v_pk_fma_f32 v[12:13], v[12:13], v[144:145], v[84:85]
	v_pk_fma_f32 v[10:11], v[10:11], v[142:143], v[82:83]
	global_store_dwordx4 v210, v[10:13], s[8:9] offset:576
	s_waitcnt vmcnt(12)
	v_pk_fma_f32 v[8:9], v[8:9], v[144:145], v[116:117]
	v_pk_fma_f32 v[6:7], v[6:7], v[142:143], v[114:115]
	global_store_dwordx4 v212, v[6:9], s[8:9] offset:576
	s_waitcnt vmcnt(11)
	v_pk_fma_f32 v[4:5], v[4:5], v[144:145], v[80:81]
	v_pk_fma_f32 v[2:3], v[2:3], v[142:143], v[78:79]
	global_store_dwordx4 v214, v[2:5], s[8:9] offset:576
	s_waitcnt vmcnt(0)
	s_and_b64 vcc, exec, s[4:5]
	s_mov_b32 s90, s6
	s_mov_b32 s18, s12
	s_mov_b64 s[10:11], s[16:17]
	s_mov_b64 s[8:9], s[14:15]
	s_cbranch_vccnz .LBB0_1509

;     __device__ __forceinline__ void operator()(const f32x4 (&acc)[2][2][4][2], const Unit& u, int wr, int wc, int fr, int fq) const {
;     ...
;         const int col0 = u.pn * BM + wc * 32 + 4 * fq, rloc = wr * 64 + fr;
; #pragma unroll
;         for (int bj = 0; bj < 2; ++bj)
; #pragma unroll
;             for (int n = 0; n < 2; ++n) { const f32x4 gv = *(const f32x4*)(gp + col0 + bj * HALF + n * 16);
; #pragma unroll
;                 for (int ai = 0; ai < 2; ++ai)
; #pragma unroll
;                     for (int m = 0; m < 4; ++m) { const size_t ro = (size_t)(rloc + ai * HALF + m * 16) * DM + col0 + bj * HALF + n * 16;
;                         if (atomic) { const f32x4 v = gv * acc[ai][bj][m][n];
; #pragma unroll
;                             for (int j = 0; j < 4; ++j) unsafeAtomicAdd(xout + ro + j, v[j]); }
;                         else { const f32x4 xi = *(const f32x4*)(xin + ro); *(f32x4*)(xout + ro) = xi + gv * acc[ai][bj][m][n]; } }
;                 asm volatile("" ::: "memory"); }
.LBB0_1865:
	s_waitcnt lgkmcnt(0)
	s_add_u32 s7, s10, s74
	s_addc_u32 s10, s11, 0
	s_ashr_i32 s21, s20, 31
	s_lshl_b64 s[4:5], s[20:21], 12
	s_add_u32 s8, s8, s4
	s_addc_u32 s9, s9, s5
	s_lshl_b64 s[4:5], s[18:19], 2
	s_add_u32 s4, s7, s4
	s_addc_u32 s5, s10, s5
	s_lshl_b32 s7, s79, 8
	s_or_b32 s7, s7, s76
	v_lshl_add_u32 v138, v137, 2, s7
	v_ashrrev_i32_e32 v139, 31, v138
	v_add_u32_e32 v140, s75, v136
	v_lshlrev_b64 v[138:139], 2, v[138:139]
	v_lshl_add_u64 v[146:147], s[4:5], 0, v[138:139]
	s_mov_b64 s[4:5], 0x26d5000
	v_ashrrev_i32_e32 v141, 31, v140
	v_lshl_add_u64 v[136:137], v[146:147], 0, s[4:5]
	s_mov_b32 s4, 0x26d5000
	v_lshlrev_b64 v[140:141], 12, v[140:141]
	v_add_co_u32_e32 v146, vcc, s4, v146
	v_lshl_add_u64 v[150:151], s[8:9], 0, v[140:141]
	s_nop 0
	v_addc_co_u32_e32 v147, vcc, 0, v147, vcc
	v_lshl_add_u64 v[154:155], v[150:151], 0, v[138:139]
	v_add_u32_e32 v200, v140, v138
	v_add_u32_e32 v202, 0x10000, v200
	v_add_u32_e32 v204, 0x20000, v200
	v_add_u32_e32 v206, 0x30000, v200
	v_add_u32_e32 v208, 0x80000, v200
	v_add_u32_e32 v210, 0x90000, v200
	v_add_u32_e32 v212, 0xa0000, v200
	v_add_u32_e32 v214, 0xb0000, v200
	global_load_dwordx4 v[146:149], v[136:137], off
	global_load_dwordx4 v[138:141], v[136:137], off offset:64
	global_load_dwordx4 v[236:239], v200, s[8:9]
	global_load_dwordx4 v[240:243], v202, s[8:9]
	global_load_dwordx4 v[244:247], v204, s[8:9]
	global_load_dwordx4 v[248:251], v206, s[8:9]
	global_load_dwordx4 v[150:153], v208, s[8:9]
	s_waitcnt vmcnt(4)
	v_pk_fma_f32 v[128:129], v[128:129], v[148:149], v[238:239]
	v_pk_fma_f32 v[126:127], v[126:127], v[146:147], v[236:237]
	global_store_dwordx4 v200, v[126:129], s[8:9]
	global_load_dwordx4 v[236:239], v210, s[8:9]
	s_waitcnt vmcnt(5)
	v_pk_fma_f32 v[124:125], v[124:125], v[148:149], v[242:243]
	v_pk_fma_f32 v[122:123], v[122:123], v[146:147], v[240:241]
	global_store_dwordx4 v202, v[122:125], s[8:9]
	global_load_dwordx4 v[240:243], v212, s[8:9]
	global_load_dwordx4 v[126:129], v214, s[8:9]
	s_waitcnt vmcnt(7)
	v_pk_fma_f32 v[120:121], v[120:121], v[148:149], v[246:247]
	v_pk_fma_f32 v[118:119], v[118:119], v[146:147], v[244:245]
	global_store_dwordx4 v204, v[118:121], s[8:9]
	global_load_dwordx4 v[244:247], v200, s[8:9] offset:64
	global_load_dwordx4 v[122:125], v202, s[8:9] offset:64
	s_waitcnt vmcnt(9)
	v_pk_fma_f32 v[116:117], v[116:117], v[148:149], v[250:251]
	v_pk_fma_f32 v[114:115], v[114:115], v[146:147], v[248:249]
	global_store_dwordx4 v206, v[114:117], s[8:9]
	global_load_dwordx4 v[248:251], v204, s[8:9] offset:64
	global_load_dwordx4 v[118:121], v206, s[8:9] offset:64
	s_waitcnt vmcnt(11)
	v_pk_fma_f32 v[112:113], v[112:113], v[148:149], v[152:153]
	v_pk_fma_f32 v[110:111], v[110:111], v[146:147], v[150:151]
	global_store_dwordx4 v208, v[110:113], s[8:9]
	global_load_dwordx4 v[150:153], v208, s[8:9] offset:64
	global_load_dwordx4 v[114:117], v210, s[8:9] offset:64
	s_waitcnt vmcnt(12)
	v_pk_fma_f32 v[108:109], v[108:109], v[148:149], v[238:239]
	v_pk_fma_f32 v[106:107], v[106:107], v[146:147], v[236:237]
	global_store_dwordx4 v210, v[106:109], s[8:9]
	global_load_dwordx4 v[236:239], v212, s[8:9] offset:64
	global_load_dwordx4 v[110:113], v214, s[8:9] offset:64
	s_waitcnt vmcnt(13)
	v_pk_fma_f32 v[104:105], v[104:105], v[148:149], v[242:243]
	v_pk_fma_f32 v[102:103], v[102:103], v[146:147], v[240:241]
	global_store_dwordx4 v212, v[102:105], s[8:9]
	global_load_dwordx4 v[240:243], v200, s[8:9] offset:512
	global_load_dwordx4 v[106:109], v202, s[8:9] offset:512
	s_waitcnt vmcnt(15)
	v_pk_fma_f32 v[100:101], v[100:101], v[148:149], v[128:129]
	v_pk_fma_f32 v[98:99], v[98:99], v[146:147], v[126:127]
	global_store_dwordx4 v214, v[98:101], s[8:9]
	global_load_dwordx4 v[146:149], v[136:137], off offset:512
	global_load_dwordx4 v[126:129], v204, s[8:9] offset:512
	global_load_dwordx4 v[102:105], v206, s[8:9] offset:512
	s_waitcnt vmcnt(17)
	v_pk_fma_f32 v[96:97], v[96:97], v[140:141], v[246:247]
	v_pk_fma_f32 v[94:95], v[94:95], v[138:139], v[244:245]
	global_store_dwordx4 v200, v[94:97], s[8:9] offset:64
	global_load_dwordx4 v[244:247], v208, s[8:9] offset:512
	s_waitcnt vmcnt(18)
	v_pk_fma_f32 v[92:93], v[92:93], v[140:141], v[124:125]
	v_pk_fma_f32 v[90:91], v[90:91], v[138:139], v[122:123]
	global_store_dwordx4 v202, v[90:93], s[8:9] offset:64
	global_load_dwordx4 v[98:101], v210, s[8:9] offset:512
	s_waitcnt vmcnt(18)
	v_pk_fma_f32 v[88:89], v[88:89], v[140:141], v[250:251]
	v_pk_fma_f32 v[86:87], v[86:87], v[138:139], v[248:249]
	global_store_dwordx4 v204, v[86:89], s[8:9] offset:64
	global_load_dwordx4 v[122:125], v212, s[8:9] offset:512
	s_waitcnt vmcnt(19)
;     __device__ __forceinline__ void operator()(const f32x4 (&acc)[2][2][4][2], const Unit& u, int wr, int wc, int fr, int fq) const {
;     ...
;         const int col0 = u.pn * BM + wc * 32 + 4 * fq, rloc = wr * 64 + fr;
; #pragma unroll
;         for (int bj = 0; bj < 2; ++bj)
; #pragma unroll
;             for (int n = 0; n < 2; ++n) { const f32x4 gv = *(const f32x4*)(gp + col0 + bj * HALF + n * 16);
; #pragma unroll
;                 for (int ai = 0; ai < 2; ++ai)
; #pragma unroll
;                     for (int m = 0; m < 4; ++m) { const size_t ro = (size_t)(rloc + ai * HALF + m * 16) * DM + col0 + bj * HALF + n * 16;
;                         if (atomic) { const f32x4 v = gv * acc[ai][bj][m][n];
; #pragma unroll
;                             for (int j = 0; j < 4; ++j) unsafeAtomicAdd(xout + ro + j, v[j]); }
;                         else { const f32x4 xi = *(const f32x4*)(xin + ro); *(f32x4*)(xout + ro) = xi + gv * acc[ai][bj][m][n]; } }
;                 asm volatile("" ::: "memory"); }
	v_pk_fma_f32 v[84:85], v[84:85], v[140:141], v[120:121]
	v_pk_fma_f32 v[82:83], v[82:83], v[138:139], v[118:119]
	global_store_dwordx4 v206, v[82:85], s[8:9] offset:64
	global_load_dwordx4 v[94:97], v214, s[8:9] offset:512
	s_waitcnt vmcnt(19)
	v_pk_fma_f32 v[80:81], v[80:81], v[140:141], v[152:153]
	v_pk_fma_f32 v[78:79], v[78:79], v[138:139], v[150:151]
	global_store_dwordx4 v208, v[78:81], s[8:9] offset:64
	global_load_dwordx4 v[248:251], v200, s[8:9] offset:576
	s_waitcnt vmcnt(20)
	v_pk_fma_f32 v[76:77], v[76:77], v[140:141], v[116:117]
	v_pk_fma_f32 v[74:75], v[74:75], v[138:139], v[114:115]
	global_store_dwordx4 v210, v[74:77], s[8:9] offset:64
	global_load_dwordx4 v[90:93], v202, s[8:9] offset:576
	s_waitcnt vmcnt(20)
	v_pk_fma_f32 v[72:73], v[72:73], v[140:141], v[238:239]
	v_pk_fma_f32 v[70:71], v[70:71], v[138:139], v[236:237]
	global_store_dwordx4 v212, v[70:73], s[8:9] offset:64
	global_load_dwordx4 v[118:121], v204, s[8:9] offset:576
	s_waitcnt vmcnt(21)
	v_pk_fma_f32 v[64:65], v[64:65], v[140:141], v[112:113]
	v_pk_fma_f32 v[62:63], v[62:63], v[138:139], v[110:111]
	global_store_dwordx4 v214, v[62:65], s[8:9] offset:64
	global_load_dwordx4 v[138:141], v[136:137], off offset:576
	global_load_dwordx4 v[86:89], v206, s[8:9] offset:576
	s_waitcnt vmcnt(19)
	v_pk_fma_f32 v[68:69], v[68:69], v[148:149], v[242:243]
	v_pk_fma_f32 v[66:67], v[66:67], v[146:147], v[240:241]
	global_store_dwordx4 v200, v[66:69], s[8:9] offset:512
	global_load_dwordx4 v[150:153], v208, s[8:9] offset:576
	s_waitcnt vmcnt(21)
	v_pk_fma_f32 v[60:61], v[60:61], v[148:149], v[108:109]
	v_pk_fma_f32 v[58:59], v[58:59], v[146:147], v[106:107]
	global_store_dwordx4 v202, v[58:61], s[8:9] offset:512
	global_load_dwordx4 v[82:85], v210, s[8:9] offset:576
	s_waitcnt vmcnt(22)
	v_pk_fma_f32 v[56:57], v[56:57], v[148:149], v[128:129]
	v_pk_fma_f32 v[54:55], v[54:55], v[146:147], v[126:127]
	global_store_dwordx4 v204, v[54:57], s[8:9] offset:512
	global_load_dwordx4 v[114:117], v212, s[8:9] offset:576
	s_waitcnt vmcnt(23)
	v_pk_fma_f32 v[52:53], v[52:53], v[148:149], v[104:105]
	v_pk_fma_f32 v[50:51], v[50:51], v[146:147], v[102:103]
	global_store_dwordx4 v206, v[50:53], s[8:9] offset:512
	global_load_dwordx4 v[78:81], v214, s[8:9] offset:576
	s_waitcnt vmcnt(23)
	v_pk_fma_f32 v[48:49], v[48:49], v[148:149], v[246:247]
	v_pk_fma_f32 v[46:47], v[46:47], v[146:147], v[244:245]
	global_store_dwordx4 v208, v[46:49], s[8:9] offset:512
	s_waitcnt vmcnt(22)
	v_pk_fma_f32 v[44:45], v[44:45], v[148:149], v[100:101]
	v_pk_fma_f32 v[42:43], v[42:43], v[146:147], v[98:99]
	global_store_dwordx4 v210, v[42:45], s[8:9] offset:512
	s_waitcnt vmcnt(21)
	v_pk_fma_f32 v[40:41], v[40:41], v[148:149], v[124:125]
	v_pk_fma_f32 v[38:39], v[38:39], v[146:147], v[122:123]
	global_store_dwordx4 v212, v[38:41], s[8:9] offset:512
	s_waitcnt vmcnt(20)
	v_pk_fma_f32 v[28:29], v[28:29], v[148:149], v[96:97]
	v_pk_fma_f32 v[26:27], v[26:27], v[146:147], v[94:95]
	global_store_dwordx4 v214, v[26:29], s[8:9] offset:512
	s_waitcnt vmcnt(13)
	v_pk_fma_f32 v[36:37], v[36:37], v[140:141], v[250:251]
	v_pk_fma_f32 v[34:35], v[34:35], v[138:139], v[248:249]
	global_store_dwordx4 v200, v[34:37], s[8:9] offset:576
	s_waitcnt vmcnt(14)
	v_pk_fma_f32 v[32:33], v[32:33], v[140:141], v[92:93]
	v_pk_fma_f32 v[30:31], v[30:31], v[138:139], v[90:91]
	global_store_dwordx4 v202, v[30:33], s[8:9] offset:576
	s_waitcnt vmcnt(15)
	v_pk_fma_f32 v[24:25], v[24:25], v[140:141], v[120:121]
	v_pk_fma_f32 v[22:23], v[22:23], v[138:139], v[118:119]
	global_store_dwordx4 v204, v[22:25], s[8:9] offset:576
	s_waitcnt vmcnt(15)
	v_pk_fma_f32 v[20:21], v[20:21], v[140:141], v[88:89]
	v_pk_fma_f32 v[18:19], v[18:19], v[138:139], v[86:87]
	global_store_dwordx4 v206, v[18:21], s[8:9] offset:576
	s_waitcnt vmcnt(14)
	v_pk_fma_f32 v[16:17], v[16:17], v[140:141], v[152:153]
	v_pk_fma_f32 v[14:15], v[14:15], v[138:139], v[150:151]
	global_store_dwordx4 v208, v[14:17], s[8:9] offset:576
	s_waitcnt vmcnt(13)
	v_pk_fma_f32 v[12:13], v[12:13], v[140:141], v[84:85]
	v_pk_fma_f32 v[10:11], v[10:11], v[138:139], v[82:83]
	global_store_dwordx4 v210, v[10:13], s[8:9] offset:576
	s_waitcnt vmcnt(12)
	v_pk_fma_f32 v[8:9], v[8:9], v[140:141], v[116:117]
	v_pk_fma_f32 v[6:7], v[6:7], v[138:139], v[114:115]
	global_store_dwordx4 v212, v[6:9], s[8:9] offset:576
	s_waitcnt vmcnt(11)
	v_pk_fma_f32 v[4:5], v[4:5], v[140:141], v[80:81]
	v_pk_fma_f32 v[2:3], v[2:3], v[138:139], v[78:79]
	global_store_dwordx4 v214, v[2:5], s[8:9] offset:576
	s_waitcnt vmcnt(0)
	s_and_b64 vcc, exec, s[2:3]
	s_mov_b32 s79, s6
	s_mov_b32 s18, s12
	s_mov_b64 s[10:11], s[16:17]
	s_mov_b64 s[8:9], s[14:15]
	s_cbranch_vccnz .LBB0_1878
